# rwkv_apply: y rows staged in LDS by the consumer waves (4 ds_write_b16 per chunk) and written out by the loader waves as 16-byte row segments, instead of 4 two-byte global stores per chunk on the crit
# speedup vs baseline: 1.0270x; 1.0206x over previous
.Lapc_loop:
	s_add_u32 s13, s4, 1
	s_lshr_b32 s5, s13, 1
	s_and_b32 s5, s5, 3
	s_mul_i32 s5, s5, 29952
	s_and_b32 s12, s13, 1
	s_mul_i32 s12, s12, 14976
	s_add_u32 s5, s5, s12
	v_add_u32_e32 v149, s5, v152
	v_add_u32_e32 v148, s5, v151
	v_add_u32_e32 v147, s5, v150
	v_mfma_f32_16x16x32_bf16 v[200:203], v[36:39], v[204:207], v[200:203]
	ds_read_u16_d16_hi v160, v149 offset:12800
	ds_read_u16_d16_hi v161, v149 offset:12928
	v_mfma_f32_16x16x32_bf16 v[168:171], v[4:7], v[204:207], v[168:171]
	ds_read_u16_d16_hi v162, v149 offset:13056
	ds_read_u16_d16_hi v163, v149 offset:13184
	v_mfma_f32_16x16x32_bf16 v[172:175], v[12:15], v[204:207], v[172:175]
	ds_read_u16_d16_hi v164, v149 offset:13312
	ds_read_b64 v[156:157], v148 offset:12288
	v_mfma_f32_16x16x32_bf16 v[176:179], v[20:23], v[204:207], v[176:179]
	ds_read_b64 v[120:121], v148 offset:8192
	ds_read_b64 v[124:125], v148 offset:8704
	v_mfma_f32_16x16x32_bf16 v[180:183], v[28:31], v[204:207], v[180:183]
	ds_read_b64 v[128:129], v148 offset:9216
	ds_read_b64 v[140:141], v148 offset:9728
	v_mfma_f32_16x16x32_bf16 v[200:203], v[40:43], v[208:211], v[200:203]
	ds_read_b128 v[112:115], v147 offset:10240
	ds_read_b128 v[116:119], v147 offset:11264
	v_mfma_f32_16x16x32_bf16 v[168:171], v[8:11], v[208:211], v[168:171]
	ds_read_b128 v[80:83], v147 offset:0
	ds_read_b128 v[84:87], v147 offset:1024
	v_mfma_f32_16x16x32_bf16 v[172:175], v[16:19], v[208:211], v[172:175]
	ds_read_b128 v[88:91], v147 offset:2048
	ds_read_b128 v[92:95], v147 offset:3072
	v_mfma_f32_16x16x32_bf16 v[176:179], v[24:27], v[208:211], v[176:179]
	ds_read_b128 v[96:99], v147 offset:4096
	ds_read_b128 v[100:103], v147 offset:5120
	v_mfma_f32_16x16x32_bf16 v[180:183], v[32:35], v[208:211], v[180:183]
	ds_read_b128 v[104:107], v147 offset:6144
	ds_read_b128 v[108:111], v147 offset:7168
	s_waitcnt lgkmcnt(15)
	v_sub_f32_e32 v216, v160, v161
	v_sub_f32_e32 v217, v161, v162
	v_sub_f32_e32 v218, v162, v163
	v_sub_f32_e32 v219, v163, v164
	v_fma_f32 v216, v76, v216, v161
	v_fma_f32 v217, v76, v217, v162
	v_fma_f32 v218, v76, v218, v163
	v_fma_f32 v219, v76, v219, v164
	v_cvt_pk_bf16_f32 v212, v216, v217
	v_cvt_pk_bf16_f32 v213, v218, v219
	s_waitcnt lgkmcnt(10)
	s_nop 1
	v_mfma_f32_16x16x32_bf16 v[224:227], v[156:159], v[212:215], 0
	v_cvt_pk_bf16_f32 v220, v200, v201
	v_cvt_pk_bf16_f32 v221, v202, v203
	v_mfma_f32_16x16x32_bf16 v[184:187], v[120:123], v[212:215], 0
	v_cvt_pk_bf16_f32 v204, v168, v169
	v_cvt_pk_bf16_f32 v205, v170, v171
	v_mfma_f32_16x16x32_bf16 v[188:191], v[124:127], v[212:215], 0
	v_cvt_pk_bf16_f32 v206, v172, v173
	v_cvt_pk_bf16_f32 v207, v174, v175
	v_mfma_f32_16x16x32_bf16 v[192:195], v[128:131], v[212:215], 0
	v_cvt_pk_bf16_f32 v208, v176, v177
	v_cvt_pk_bf16_f32 v209, v178, v179
	v_mfma_f32_16x16x32_bf16 v[196:199], v[140:143], v[212:215], 0
	v_cvt_pk_bf16_f32 v210, v180, v181
	v_cvt_pk_bf16_f32 v211, v182, v183
	s_add_u32 s12, s4, 1
	s_lshr_b32 s12, s12, 1
	s_and_b32 s12, s12, 1
	s_lshl_b32 s12, s12, 12
	s_bitcmp1_b32 s4, 0
	s_cselect_b32 s8, 0, 0x800
	s_add_u32 s12, s12, s8
	s_add_u32 s12, s12, 119808
	v_add_u32_e32 v219, s12, v152
	ds_write_b16 v219, v220 offset:0
	ds_write_b16_d16_hi v219, v220 offset:128
	ds_write_b16 v219, v221 offset:256
	ds_write_b16_d16_hi v219, v221 offset:384
	s_waitcnt lgkmcnt(0)
	s_barrier
	s_add_u32 s4, s4, 2
	s_cmp_lt_u32 s4, 256
	s_cbranch_scc0 .Lapc_last
	s_lshr_b32 s5, s4, 1
	s_and_b32 s5, s5, 3
	s_mul_i32 s5, s5, 29952
	s_and_b32 s12, s4, 1
	s_mul_i32 s12, s12, 14976
	s_add_u32 s5, s5, s12
	v_add_u32_e32 v149, s5, v152
	v_add_u32_e32 v148, s5, v151
	v_add_u32_e32 v147, s5, v150
	v_mfma_f32_16x16x32_bf16 v[224:227], v[112:115], v[204:207], v[224:227]
	ds_read_u16_d16_hi v64, v149 offset:12800
	ds_read_u16_d16_hi v65, v149 offset:12928
	v_mfma_f32_16x16x32_bf16 v[184:187], v[80:83], v[204:207], v[184:187]
	ds_read_u16_d16_hi v66, v149 offset:13056
	ds_read_u16_d16_hi v67, v149 offset:13184
	v_mfma_f32_16x16x32_bf16 v[188:191], v[88:91], v[204:207], v[188:191]
	ds_read_u16_d16_hi v68, v149 offset:13312
	ds_read_b64 v[60:61], v148 offset:12288
	v_mfma_f32_16x16x32_bf16 v[192:195], v[96:99], v[204:207], v[192:195]
	ds_read_b64 v[44:45], v148 offset:8192
	ds_read_b64 v[48:49], v148 offset:8704
	v_mfma_f32_16x16x32_bf16 v[196:199], v[104:107], v[204:207], v[196:199]
	ds_read_b64 v[52:53], v148 offset:9216
	ds_read_b64 v[56:57], v148 offset:9728
	v_mfma_f32_16x16x32_bf16 v[224:227], v[116:119], v[208:211], v[224:227]
	ds_read_b128 v[36:39], v147 offset:10240
	ds_read_b128 v[40:43], v147 offset:11264
	v_mfma_f32_16x16x32_bf16 v[184:187], v[84:87], v[208:211], v[184:187]
	ds_read_b128 v[4:7], v147 offset:0
	ds_read_b128 v[8:11], v147 offset:1024
	v_mfma_f32_16x16x32_bf16 v[188:191], v[92:95], v[208:211], v[188:191]
	ds_read_b128 v[12:15], v147 offset:2048
	ds_read_b128 v[16:19], v147 offset:3072
	v_mfma_f32_16x16x32_bf16 v[192:195], v[100:103], v[208:211], v[192:195]
	ds_read_b128 v[20:23], v147 offset:4096
	ds_read_b128 v[24:27], v147 offset:5120
	v_mfma_f32_16x16x32_bf16 v[196:199], v[108:111], v[208:211], v[196:199]
	ds_read_b128 v[28:31], v147 offset:6144
	ds_read_b128 v[32:35], v147 offset:7168
	s_waitcnt lgkmcnt(15)
	v_sub_f32_e32 v216, v64, v65
	v_sub_f32_e32 v217, v65, v66
	v_sub_f32_e32 v218, v66, v67
	v_sub_f32_e32 v219, v67, v68
	v_fma_f32 v216, v76, v216, v65
	v_fma_f32 v217, v76, v217, v66
	v_fma_f32 v218, v76, v218, v67
	v_fma_f32 v219, v76, v219, v68
	v_cvt_pk_bf16_f32 v212, v216, v217
	v_cvt_pk_bf16_f32 v213, v218, v219
	s_waitcnt lgkmcnt(10)
	s_nop 1
	v_mfma_f32_16x16x32_bf16 v[200:203], v[60:63], v[212:215], 0
	v_cvt_pk_bf16_f32 v220, v224, v225
	v_cvt_pk_bf16_f32 v221, v226, v227
	v_mfma_f32_16x16x32_bf16 v[168:171], v[44:47], v[212:215], 0
	v_cvt_pk_bf16_f32 v204, v184, v185
	v_cvt_pk_bf16_f32 v205, v186, v187
	v_mfma_f32_16x16x32_bf16 v[172:175], v[48:51], v[212:215], 0
	v_cvt_pk_bf16_f32 v206, v188, v189
	v_cvt_pk_bf16_f32 v207, v190, v191
	v_mfma_f32_16x16x32_bf16 v[176:179], v[52:55], v[212:215], 0
	v_cvt_pk_bf16_f32 v208, v192, v193
	v_cvt_pk_bf16_f32 v209, v194, v195
	v_mfma_f32_16x16x32_bf16 v[180:183], v[56:59], v[212:215], 0
	v_cvt_pk_bf16_f32 v210, v196, v197
	v_cvt_pk_bf16_f32 v211, v198, v199
	s_add_u32 s12, s13, 1
	s_lshr_b32 s12, s12, 1
	s_and_b32 s12, s12, 1
	s_lshl_b32 s12, s12, 12
	s_bitcmp1_b32 s13, 0
	s_cselect_b32 s8, 0, 0x800
	s_add_u32 s12, s12, s8
	s_add_u32 s12, s12, 119808
	v_add_u32_e32 v219, s12, v152
	ds_write_b16 v219, v220 offset:0
	ds_write_b16_d16_hi v219, v220 offset:128
	ds_write_b16 v219, v221 offset:256
	ds_write_b16_d16_hi v219, v221 offset:384
	s_waitcnt lgkmcnt(0)
	s_branch .Lapc_loop

.Lld_wdone:
	s_lshl_b32 s15, s3, 6
	v_add_u32_e32 v6, s15, v146
	v_lshrrev_b32_e32 v7, 3, v6
	v_and_b32_e32 v6, 7, v6
	v_lshlrev_b32_e32 v3, 7, v7
	v_lshl_add_u32 v3, v6, 4, v3
	v_lshlrev_b32_e32 v5, 11, v7
	v_lshl_add_u32 v5, v6, 4, v5
	s_lshr_b32 s15, s2, 4
	s_lshl_b32 s15, s15, 23
	s_and_b32 s20, s2, 15
	s_lshl_b32 s20, s20, 7
	s_add_u32 s15, s15, s20
	s_add_u32 s68, s52, s15
	s_addc_u32 s69, s53, 0
	s_add_u32 s68, s68, 0x7ff8000
	s_addc_u32 s69, s69, 0
	s_cmp_ge_u32 s3, 2
	s_cselect_b32 s72, -1, 0
	s_cselect_b32 s73, -1, 0
	s_mov_b32 s15, 0
	s_and_b32 s22, s15, 3
	s_mul_i32 s22, s22, 29952
	s_lshl_b32 s20, s15, 1
	s_mul_i32 s23, s20, 0x3200
	s_add_u32 s28, s4, s23
	s_addc_u32 s29, s5, 0
	s_mul_i32 s23, s20, s8
	s_add_u32 s64, s6, s23
	s_addc_u32 s65, s7, 0
	s_add_u32 s26, s22, s10
	s_mov_b32 m0, s26
	s_nop 0
	global_load_lds_dwordx4 v0, s[28:29]
	s_add_u32 s28, s28, 0x1000
	s_addc_u32 s29, s29, 0
	s_add_i32 m0, s26, 0x1000
	s_nop 0
	global_load_lds_dwordx4 v0, s[28:29]
	s_add_u32 s28, s28, 0x1000
	s_addc_u32 s29, s29, 0
	s_add_i32 m0, s26, 0x2000
	s_nop 0
	global_load_lds_dwordx4 v0, s[28:29]
	s_add_i32 m0, s22, s9
	s_mov_b64 exec, s[12:13]
	global_load_lds_dwordx4 v1, s[64:65]
	s_mov_b64 exec, -1
	s_add_u32 s20, s20, 1
	s_add_u32 s22, s22, 14976
	s_mul_i32 s23, s20, 0x3200
	s_add_u32 s28, s4, s23
	s_addc_u32 s29, s5, 0
	s_mul_i32 s23, s20, s8
	s_add_u32 s64, s6, s23
	s_addc_u32 s65, s7, 0
	s_add_u32 s26, s22, s10
	s_mov_b32 m0, s26
	s_nop 0
	global_load_lds_dwordx4 v0, s[28:29]
	s_add_u32 s28, s28, 0x1000
	s_addc_u32 s29, s29, 0
	s_add_i32 m0, s26, 0x1000
	s_nop 0
	global_load_lds_dwordx4 v0, s[28:29]
	s_add_u32 s28, s28, 0x1000
	s_addc_u32 s29, s29, 0
	s_add_i32 m0, s26, 0x2000
	s_nop 0
	global_load_lds_dwordx4 v0, s[28:29]
	s_add_i32 m0, s22, s9
	s_mov_b64 exec, s[12:13]
	global_load_lds_dwordx4 v1, s[64:65]
	s_mov_b64 exec, -1
	s_mov_b32 s15, 1
	s_and_b32 s22, s15, 3
	s_mul_i32 s22, s22, 29952
	s_lshl_b32 s20, s15, 1
	s_mul_i32 s23, s20, 0x3200
	s_add_u32 s28, s4, s23
	s_addc_u32 s29, s5, 0
	s_mul_i32 s23, s20, s8
	s_add_u32 s64, s6, s23
	s_addc_u32 s65, s7, 0
	s_add_u32 s26, s22, s10
	s_mov_b32 m0, s26
	s_nop 0
	global_load_lds_dwordx4 v0, s[28:29]
	s_add_u32 s28, s28, 0x1000
	s_addc_u32 s29, s29, 0
	s_add_i32 m0, s26, 0x1000
	s_nop 0
	global_load_lds_dwordx4 v0, s[28:29]
	s_add_u32 s28, s28, 0x1000
	s_addc_u32 s29, s29, 0
	s_add_i32 m0, s26, 0x2000
	s_nop 0
	global_load_lds_dwordx4 v0, s[28:29]
	s_add_i32 m0, s22, s9
	s_mov_b64 exec, s[12:13]
	global_load_lds_dwordx4 v1, s[64:65]
	s_mov_b64 exec, -1
	s_add_u32 s20, s20, 1
	s_add_u32 s22, s22, 14976
	s_mul_i32 s23, s20, 0x3200
	s_add_u32 s28, s4, s23
	s_addc_u32 s29, s5, 0
	s_mul_i32 s23, s20, s8
	s_add_u32 s64, s6, s23
	s_addc_u32 s65, s7, 0
	s_add_u32 s26, s22, s10
	s_mov_b32 m0, s26
	s_nop 0
	global_load_lds_dwordx4 v0, s[28:29]
	s_add_u32 s28, s28, 0x1000
	s_addc_u32 s29, s29, 0
	s_add_i32 m0, s26, 0x1000
	s_nop 0
	global_load_lds_dwordx4 v0, s[28:29]
	s_add_u32 s28, s28, 0x1000
	s_addc_u32 s29, s29, 0
	s_add_i32 m0, s26, 0x2000
	s_nop 0
	global_load_lds_dwordx4 v0, s[28:29]
	s_add_i32 m0, s22, s9
	s_mov_b64 exec, s[12:13]
	global_load_lds_dwordx4 v1, s[64:65]
	s_mov_b64 exec, -1
	s_mov_b32 s15, 2
	s_and_b32 s22, s15, 3
	s_mul_i32 s22, s22, 29952
	s_lshl_b32 s20, s15, 1
	s_mul_i32 s23, s20, 0x3200
	s_add_u32 s28, s4, s23
	s_addc_u32 s29, s5, 0
	s_mul_i32 s23, s20, s8
	s_add_u32 s64, s6, s23
	s_addc_u32 s65, s7, 0
	s_add_u32 s26, s22, s10
	s_mov_b32 m0, s26
	s_nop 0
	global_load_lds_dwordx4 v0, s[28:29]
	s_add_u32 s28, s28, 0x1000
	s_addc_u32 s29, s29, 0
	s_add_i32 m0, s26, 0x1000
	s_nop 0
	global_load_lds_dwordx4 v0, s[28:29]
	s_add_u32 s28, s28, 0x1000
	s_addc_u32 s29, s29, 0
	s_add_i32 m0, s26, 0x2000
	s_nop 0
	global_load_lds_dwordx4 v0, s[28:29]
	s_add_i32 m0, s22, s9
	s_mov_b64 exec, s[12:13]
	global_load_lds_dwordx4 v1, s[64:65]
	s_mov_b64 exec, -1
	s_add_u32 s20, s20, 1
	s_add_u32 s22, s22, 14976
	s_mul_i32 s23, s20, 0x3200
	s_add_u32 s28, s4, s23
	s_addc_u32 s29, s5, 0
	s_mul_i32 s23, s20, s8
	s_add_u32 s64, s6, s23
	s_addc_u32 s65, s7, 0
	s_add_u32 s26, s22, s10
	s_mov_b32 m0, s26
	s_nop 0
	global_load_lds_dwordx4 v0, s[28:29]
	s_add_u32 s28, s28, 0x1000
	s_addc_u32 s29, s29, 0
	s_add_i32 m0, s26, 0x1000
	s_nop 0
	global_load_lds_dwordx4 v0, s[28:29]
	s_add_u32 s28, s28, 0x1000
	s_addc_u32 s29, s29, 0
	s_add_i32 m0, s26, 0x2000
	s_nop 0
	global_load_lds_dwordx4 v0, s[28:29]
	s_add_i32 m0, s22, s9
	s_mov_b64 exec, s[12:13]
	global_load_lds_dwordx4 v1, s[64:65]
	s_mov_b64 exec, -1
	s_waitcnt vmcnt(16)
	s_barrier
	s_mov_b32 s14, 0

.Lld_bar:
	s_barrier
	s_and_b32 s15, s14, 1
	s_lshl_b32 s15, s15, 12
	s_add_u32 s15, s15, 119808
	v_add_u32_e32 v4, s15, v3
	ds_read_b128 v[8:11], v4
	s_lshl_b32 s15, s14, 16
	s_add_u32 s66, s68, s15
	s_addc_u32 s67, s69, 0
	s_cmp_eq_u32 s14, 0
	s_cselect_b32 s70, s72, -1
	s_cselect_b32 s71, s73, -1
	s_waitcnt lgkmcnt(0)
	s_mov_b64 exec, s[70:71]
	global_store_dwordx4 v5, v[8:11], s[66:67]
	s_mov_b64 exec, -1
	s_add_u32 s14, s14, 1
	s_cmp_lt_u32 s14, 128
	s_cbranch_scc1 .Lld_loop
